# prompt attention softmax VALU trim (max3 tree, packed subtract) on top of LDS b128 fragment layouts
# speedup vs baseline: 1.0104x; 1.0020x over previous
.LBB0_1771:
	s_nop 3
	v_max3_f32 v64, v56, v57, v58
	v_max3_f32 v64, v64, v59, v52
	v_max3_f32 v64, v64, v53, v54
	v_max3_f32 v64, v64, v55, v48
	v_max3_f32 v64, v64, v49, v50
	v_max3_f32 v64, v64, v51, v44
	v_max3_f32 v64, v64, v45, v46
	v_max3_f32 v64, v64, v47, s76
	ds_bpermute_b32 v65, v103, v64
	v_add_u32_e32 v114, 0x3000, v94
	v_add_u32_e32 v115, 0x3000, v95
	v_add_u32_e32 v116, 0x3000, v96
	v_add_u32_e32 v117, 0x3000, v97
	s_waitcnt lgkmcnt(0)
	v_max_f32_e32 v64, v64, v65
	ds_bpermute_b32 v65, v104, v64
	s_waitcnt lgkmcnt(0)
	v_max3_f32 v69, v107, v64, v65
	v_sub_f32_e32 v64, v107, v69
	v_pk_add_f32 v[56:57], v[56:57], v[68:69] op_sel:[0,1] op_sel_hi:[1,1] neg_lo:[0,1] neg_hi:[0,1]
	v_pk_add_f32 v[58:59], v[58:59], v[68:69] op_sel:[0,1] op_sel_hi:[1,1] neg_lo:[0,1] neg_hi:[0,1]
	v_pk_add_f32 v[52:53], v[52:53], v[68:69] op_sel:[0,1] op_sel_hi:[1,1] neg_lo:[0,1] neg_hi:[0,1]
	v_pk_add_f32 v[54:55], v[54:55], v[68:69] op_sel:[0,1] op_sel_hi:[1,1] neg_lo:[0,1] neg_hi:[0,1]
	v_pk_add_f32 v[48:49], v[48:49], v[68:69] op_sel:[0,1] op_sel_hi:[1,1] neg_lo:[0,1] neg_hi:[0,1]
	v_pk_add_f32 v[50:51], v[50:51], v[68:69] op_sel:[0,1] op_sel_hi:[1,1] neg_lo:[0,1] neg_hi:[0,1]
	v_pk_add_f32 v[44:45], v[44:45], v[68:69] op_sel:[0,1] op_sel_hi:[1,1] neg_lo:[0,1] neg_hi:[0,1]
	v_pk_add_f32 v[46:47], v[46:47], v[68:69] op_sel:[0,1] op_sel_hi:[1,1] neg_lo:[0,1] neg_hi:[0,1]
	v_exp_f32_e32 v56, v56
	v_exp_f32_e32 v57, v57
	v_exp_f32_e32 v58, v58
	v_exp_f32_e32 v59, v59
	v_exp_f32_e32 v52, v52
	v_exp_f32_e32 v53, v53
	v_exp_f32_e32 v54, v54
	v_exp_f32_e32 v55, v55
	v_exp_f32_e32 v70, v48
	v_exp_f32_e32 v71, v49
	v_exp_f32_e32 v107, v50
	v_exp_f32_e32 v108, v51
	v_exp_f32_e32 v109, v44
	v_exp_f32_e32 v110, v45
	v_exp_f32_e32 v111, v46
	v_exp_f32_e32 v112, v47
	v_exp_f32_e32 v68, v64
	v_add_f32_e32 v65, v56, v57
	v_add_f32_e32 v65, v58, v65
	v_add_f32_e32 v65, v59, v65
	v_add_f32_e32 v65, v52, v65
	v_add_f32_e32 v65, v53, v65
	v_add_f32_e32 v65, v54, v65
	v_add_f32_e32 v65, v55, v65
	v_add_f32_e32 v48, v70, v65
	v_add_f32_e32 v48, v71, v48
	v_add_f32_e32 v48, v107, v48
	v_add_f32_e32 v48, v108, v48
	v_add_f32_e32 v44, v109, v48
	v_add_f32_e32 v44, v110, v44
	v_add_f32_e32 v44, v111, v44
	v_add_f32_e32 v113, v112, v44
	v_cvt_pk_bf16_f32 v44, v56, v57
	v_cvt_pk_bf16_f32 v45, v58, v59
	v_cvt_pk_bf16_f32 v46, v52, v53
	v_cvt_pk_bf16_f32 v47, v54, v55
	ds_read_b128 v[48:51], v114 offset:1024
	ds_read_b128 v[52:55], v115 offset:1024
	ds_read_b128 v[56:59], v116 offset:1024
	ds_read_b128 v[64:67], v117 offset:1024
	v_pk_mul_f32 v[38:39], v[38:39], v[68:69] op_sel_hi:[1,0]
	v_pk_mul_f32 v[36:37], v[36:37], v[68:69] op_sel_hi:[1,0]
	v_pk_mul_f32 v[34:35], v[34:35], v[68:69] op_sel_hi:[1,0]
	v_pk_mul_f32 v[32:33], v[32:33], v[68:69] op_sel_hi:[1,0]
	v_pk_mul_f32 v[30:31], v[30:31], v[68:69] op_sel_hi:[1,0]
	v_pk_mul_f32 v[28:29], v[28:29], v[68:69] op_sel_hi:[1,0]
	v_pk_mul_f32 v[42:43], v[42:43], v[68:69] op_sel_hi:[1,0]
	v_pk_mul_f32 v[40:41], v[40:41], v[68:69] op_sel_hi:[1,0]
	s_waitcnt lgkmcnt(3)
	v_mfma_f32_16x16x32_bf16 v[36:39], v[48:51], v[44:47], v[36:39]
	s_waitcnt lgkmcnt(2)
	v_mfma_f32_16x16x32_bf16 v[32:35], v[52:55], v[44:47], v[32:35]
	s_waitcnt lgkmcnt(1)
	v_mfma_f32_16x16x32_bf16 v[28:31], v[56:59], v[44:47], v[28:31]
	s_waitcnt lgkmcnt(0)
	v_mfma_f32_16x16x32_bf16 v[40:43], v[64:67], v[44:47], v[40:43]
	ds_read_b128 v[48:51], v114 offset:1088
	ds_read_b128 v[52:55], v115 offset:1088
	ds_read_b128 v[56:59], v116 offset:1088
	ds_read_b128 v[64:67], v117 offset:1088
	v_cvt_pk_bf16_f32 v44, v70, v71
	v_cvt_pk_bf16_f32 v45, v107, v108
	v_cvt_pk_bf16_f32 v46, v109, v110
	v_cvt_pk_bf16_f32 v47, v111, v112
	s_waitcnt lgkmcnt(3)
	v_mfma_f32_16x16x32_bf16 v[36:39], v[48:51], v[44:47], v[36:39]
	v_fmac_f32_e32 v113, v0, v68
	v_mov_b32_e32 v107, v69
	v_mov_b32_e32 v0, v113
	s_waitcnt lgkmcnt(2)
	v_mfma_f32_16x16x32_bf16 v[32:35], v[52:55], v[44:47], v[32:35]
	s_waitcnt lgkmcnt(1)
	v_mfma_f32_16x16x32_bf16 v[28:31], v[56:59], v[44:47], v[28:31]
	s_waitcnt lgkmcnt(0)
	v_mfma_f32_16x16x32_bf16 v[40:43], v[64:67], v[44:47], v[40:43]
